# rwkv in-proj k-loop restructured: LDS double buffer, one barrier per k-tile, MFMAs of tile k woven into the mix VALU of tile k+1, next-tile loads issued progressively
# speedup vs baseline: 1.1432x; 1.0066x over previous
.LBB0_757:
	s_or_b64 exec, exec, s[24:25]
	s_lshr_b32 s24, s28, 3
	s_sub_i32 s25, s28, 21
	s_cmp_lt_i32 s28, 24
	s_cselect_b32 s24, s24, s25
	s_lshl_b32 s58, s24, 10
	v_lshlrev_b64 v[8:9], 11, v[8:9]
	s_mov_b64 s[24:25], 0x30000
	v_lshl_add_u64 v[8:9], v[8:9], 0, s[24:25]
	v_lshl_add_u64 v[18:19], v[126:127], 0, v[8:9]
	global_load_dwordx4 v[112:115], v[18:19], off
	v_add_u32_e32 v3, 0xffff0000, v2
	v_lshrrev_b32_e32 v20, 5, v3
	v_add_u32_e32 v3, 0xffff0020, v2
	v_add_u32_e32 v18, -1, v2
	v_cmp_lt_i32_e32 vcc, s70, v2
	v_add_u32_e32 v22, 31, v2
	v_cmp_lt_i32_e64 s[24:25], s71, v2
	v_lshrrev_b32_e32 v24, 5, v3
	v_add_u32_e32 v26, 63, v2
	v_cmp_lt_i32_e64 s[26:27], s72, v2
	v_add_u32_e32 v3, 0xffff0040, v2
	v_add_u32_e32 v30, 0x5f, v2
	v_cmp_lt_i32_e64 s[28:29], s73, v2
	v_add_u32_e32 v2, 0xffff0060, v2
	v_ashrrev_i32_e32 v19, 31, v18
	v_mov_b32_e32 v21, v64
	v_ashrrev_i32_e32 v23, 31, v22
	v_mov_b32_e32 v25, v64
	v_ashrrev_i32_e32 v27, 31, v26
	v_lshrrev_b32_e32 v28, 5, v3
	v_mov_b32_e32 v29, v64
	v_ashrrev_i32_e32 v31, 31, v30
	v_lshrrev_b32_e32 v2, 5, v2
	v_mov_b32_e32 v3, v64
	s_ashr_i32 s59, s58, 31
	v_lshlrev_b64 v[18:19], 11, v[18:19]
	v_lshlrev_b64 v[20:21], 12, v[20:21]
	v_lshlrev_b64 v[22:23], 11, v[22:23]
	v_lshlrev_b64 v[24:25], 12, v[24:25]
	v_lshlrev_b64 v[26:27], 11, v[26:27]
	v_lshlrev_b64 v[28:29], 12, v[28:29]
	v_lshlrev_b64 v[30:31], 11, v[30:31]
	v_lshlrev_b64 v[2:3], 12, v[2:3]
	v_lshl_add_u64 v[142:143], s[56:57], 0, v[0:1]
	v_mov_b32_e32 v0, 0
	v_lshl_add_u64 v[134:135], s[4:5], 0, v[4:5]
	v_lshl_add_u64 v[136:137], s[4:5], 0, v[10:11]
	v_lshl_add_u64 v[138:139], s[4:5], 0, v[16:17]
	v_lshl_add_u64 v[140:141], s[4:5], 0, v[8:9]
	v_lshl_add_u64 v[144:145], s[56:57], 0, v[18:19]
	v_lshl_add_u64 v[146:147], s[56:57], 0, v[6:7]
	v_lshl_add_u64 v[148:149], s[56:57], 0, v[22:23]
	v_lshl_add_u64 v[150:151], s[56:57], 0, v[12:13]
	v_lshl_add_u64 v[188:189], s[56:57], 0, v[26:27]
	v_lshl_add_u64 v[190:191], s[56:57], 0, v[14:15]
	v_lshl_add_u64 v[192:193], s[56:57], 0, v[30:31]
	v_lshl_add_u64 v[194:195], v[130:131], 0, v[20:21]
	v_lshl_add_u64 v[196:197], v[130:131], 0, v[24:25]
	v_lshl_add_u64 v[198:199], v[130:131], 0, v[28:29]
	v_lshl_add_u64 v[200:201], v[130:131], 0, v[2:3]
	v_lshl_add_u64 v[202:203], s[58:59], 2, v[132:133]
	s_mov_b64 s[58:59], 0
	v_mov_b32_e32 v1, v0
	v_mov_b32_e32 v2, v0
	v_mov_b32_e32 v3, v0
	v_mov_b32_e32 v4, v0
	v_mov_b32_e32 v5, v0
	v_mov_b32_e32 v6, v0
	v_mov_b32_e32 v7, v0
	v_mov_b32_e32 v8, v0
	v_mov_b32_e32 v9, v0
	v_mov_b32_e32 v10, v0
	v_mov_b32_e32 v11, v0
	v_mov_b32_e32 v12, v0
	v_mov_b32_e32 v13, v0
	v_mov_b32_e32 v14, v0
	v_mov_b32_e32 v15, v0
	v_mov_b32_e32 v48, v0
	v_mov_b32_e32 v49, v0
	v_mov_b32_e32 v50, v0
	v_mov_b32_e32 v51, v0
	v_mov_b32_e32 v52, v0
	v_mov_b32_e32 v53, v0
	v_mov_b32_e32 v54, v0
	v_mov_b32_e32 v55, v0
	v_mov_b32_e32 v56, v0
	v_mov_b32_e32 v57, v0
	v_mov_b32_e32 v58, v0
	v_mov_b32_e32 v59, v0
	v_mov_b32_e32 v60, v0
	v_mov_b32_e32 v61, v0
	v_mov_b32_e32 v62, v0
	v_mov_b32_e32 v63, v0
	v_mov_b32_e32 v32, v0
	v_mov_b32_e32 v33, v0
	v_mov_b32_e32 v34, v0
	v_mov_b32_e32 v35, v0
	v_mov_b32_e32 v36, v0
	v_mov_b32_e32 v37, v0
	v_mov_b32_e32 v38, v0
	v_mov_b32_e32 v39, v0
	v_mov_b32_e32 v40, v0
	v_mov_b32_e32 v41, v0
	v_mov_b32_e32 v42, v0
	v_mov_b32_e32 v43, v0
	v_mov_b32_e32 v44, v0
	v_mov_b32_e32 v45, v0
	v_mov_b32_e32 v46, v0
	v_mov_b32_e32 v47, v0
	v_mov_b32_e32 v16, v0
	v_mov_b32_e32 v17, v0
	v_mov_b32_e32 v18, v0
	v_mov_b32_e32 v19, v0
	v_mov_b32_e32 v20, v0
	v_mov_b32_e32 v21, v0
	v_mov_b32_e32 v22, v0
	v_mov_b32_e32 v23, v0
	v_mov_b32_e32 v24, v0
	v_mov_b32_e32 v25, v0
	v_mov_b32_e32 v26, v0
	v_mov_b32_e32 v27, v0
	v_mov_b32_e32 v28, v0
	v_mov_b32_e32 v29, v0
	v_mov_b32_e32 v30, v0
	v_mov_b32_e32 v31, v0
	v_readfirstlane_b32 s98, v202
	v_readfirstlane_b32 s99, v203
	v_lshlrev_b32_e32 v120, 4, v156
	s_nop 3
	global_load_dwordx4 v[116:119], v120, s[98:99]
	v_and_b32_e32 v255, 7, v156
	v_lshlrev_b32_e32 v255, 5, v255
	v_add_u32_e32 v255, 0x12000, v255
	v_add_u32_e32 v121, 0x12000, v120
	s_waitcnt vmcnt(0)
	ds_write_b128 v121, v[116:119]
	s_waitcnt lgkmcnt(0)
	s_branch .LBB0_761
.LBB0_761:
	s_barrier
	ds_read_b128 v[230:233], v255 offset:16
	ds_read_b128 v[234:237], v255
	v_add_u32_e32 v255, 0x100, v255
	s_waitcnt vmcnt(9)
	v_lshlrev_b32_e32 v65, 16, v68
	v_lshlrev_b32_e32 v66, 16, v72
	v_sub_f32_e32 v66, v66, v65
	v_and_b32_e32 v67, 0xffff0000, v72
	v_lshlrev_b32_e32 v221, 16, v73
	v_and_b32_e32 v238, 0xffff0000, v73
	v_lshlrev_b32_e32 v240, 16, v70
	v_and_b32_e32 v241, 0xffff0000, v70
	v_lshlrev_b32_e32 v242, 16, v71
	v_and_b32_e32 v243, 0xffff0000, v71
	s_waitcnt vmcnt(6) lgkmcnt(0)
	v_fmac_f32_e32 v65, v234, v66
	v_and_b32_e32 v66, 0xffff0000, v68
	v_sub_f32_e32 v67, v67, v66
	v_fmac_f32_e32 v66, v67, v235
	v_lshlrev_b32_e32 v67, 16, v69
	v_sub_f32_e32 v221, v221, v67
	v_fmac_f32_e32 v67, v221, v236
	v_and_b32_e32 v221, 0xffff0000, v69
	v_sub_f32_e32 v238, v238, v221
	v_fmac_f32_e32 v221, v238, v237
	v_lshlrev_b32_e32 v238, 16, v74
	v_sub_f32_e32 v238, v238, v240
	v_fmac_f32_e32 v240, v238, v230
	v_and_b32_e32 v238, 0xffff0000, v74
	v_sub_f32_e32 v238, v238, v241
	v_fmac_f32_e32 v241, v238, v231
	v_lshlrev_b32_e32 v238, 16, v75
	v_sub_f32_e32 v238, v238, v242
	v_fmac_f32_e32 v242, v238, v232
	v_and_b32_e32 v238, 0xffff0000, v75
	v_sub_f32_e32 v238, v238, v243
	v_fmac_f32_e32 v243, v238, v233
	v_cvt_pk_bf16_f32 v238, v65, v66
	v_lshlrev_b32_e32 v65, 16, v80
	v_lshlrev_b32_e32 v66, 16, v84
	v_sub_f32_e32 v66, v66, v65
	v_cvt_pk_bf16_f32 v239, v67, v221
	v_fmac_f32_e32 v65, v66, v234
	v_and_b32_e32 v66, 0xffff0000, v80
	v_and_b32_e32 v67, 0xffff0000, v84
	v_sub_f32_e32 v67, v67, v66
	v_fmac_f32_e32 v66, v67, v235
	v_lshlrev_b32_e32 v67, 16, v81
	v_lshlrev_b32_e32 v221, 16, v85
	v_cvt_pk_bf16_f32 v240, v240, v241
	v_cvt_pk_bf16_f32 v241, v242, v243
	v_sub_f32_e32 v221, v221, v67
	ds_write_b128 v161, v[238:241]
	ds_write_b128 v161, v[76:79] offset:18432
	s_cmpk_eq_i32 s58, 0xf00
	s_cbranch_scc0 .Lrmp_Lrin_do_a
	s_waitcnt vmcnt(0)
	s_branch .Lrmp_Lrin_skip_a
.Lrmp_Lrin_do_a:
	v_lshl_add_u64 v[246:247], v[142:143], 0, v[186:187]
	global_load_dwordx4 v[68:71], v[246:247], off
	s_and_saveexec_b64 s[60:61], s[16:17]
	s_xor_b64 s[60:61], exec, s[60:61]
	s_cbranch_execz .Lrmp_b764
	v_lshl_add_u64 v[246:247], v[144:145], 0, v[186:187]
	global_load_dwordx4 v[72:75], v[246:247], off
.Lrmp_b764:
	s_andn2_saveexec_b64 s[60:61], s[60:61]
	s_cbranch_execz .Lrmp_b768
	s_waitcnt vmcnt(0)
	v_mov_b32_e32 v72, v64
	v_mov_b32_e32 v73, v64
	v_mov_b32_e32 v74, v64
	v_mov_b32_e32 v75, v64
	s_and_saveexec_b64 s[62:63], vcc
	s_cbranch_execz .Lrmp_b767
	v_lshl_add_u64 v[246:247], v[194:195], 0, s[58:59]
	global_load_dwordx4 v[72:75], v[246:247], off offset:256
	global_load_dwordx4 v[76:79], v[246:247], off offset:272
	s_waitcnt vmcnt(1)
	v_cvt_pk_bf16_f32 v72, v72, v73
	v_cvt_pk_bf16_f32 v73, v74, v75
	s_waitcnt vmcnt(0)
	v_cvt_pk_bf16_f32 v74, v76, v77
	v_cvt_pk_bf16_f32 v75, v78, v79

.Lrmp_b768:
	s_or_b64 exec, exec, s[60:61]
	v_lshl_add_u64 v[246:247], v[134:135], 0, v[186:187]
	global_load_dwordx4 v[76:79], v[246:247], off
.Lrmp_Lrin_skip_a:
	v_fmac_f32_e32 v67, v221, v236
	v_and_b32_e32 v221, 0xffff0000, v81
	v_and_b32_e32 v238, 0xffff0000, v85
	v_sub_f32_e32 v238, v238, v221
	v_fmac_f32_e32 v221, v238, v237
	v_lshlrev_b32_e32 v240, 16, v82
	v_lshlrev_b32_e32 v238, 16, v86
	v_sub_f32_e32 v238, v238, v240
	v_fmac_f32_e32 v240, v238, v230
	v_and_b32_e32 v241, 0xffff0000, v82
	v_and_b32_e32 v238, 0xffff0000, v86
	v_sub_f32_e32 v238, v238, v241
	v_fmac_f32_e32 v241, v238, v231
	v_lshlrev_b32_e32 v242, 16, v83
	v_lshlrev_b32_e32 v238, 16, v87
	v_sub_f32_e32 v238, v238, v242
	v_fmac_f32_e32 v242, v238, v232
	v_and_b32_e32 v243, 0xffff0000, v83
	v_and_b32_e32 v238, 0xffff0000, v87
	v_sub_f32_e32 v238, v238, v243
	v_fmac_f32_e32 v243, v238, v233
	v_cvt_pk_bf16_f32 v238, v65, v66
	s_waitcnt vmcnt(6)
	v_lshlrev_b32_e32 v65, 16, v92
	v_lshlrev_b32_e32 v66, 16, v96
	v_sub_f32_e32 v66, v66, v65
	v_cvt_pk_bf16_f32 v239, v67, v221
	v_fmac_f32_e32 v65, v66, v234
	v_and_b32_e32 v66, 0xffff0000, v92
	v_and_b32_e32 v67, 0xffff0000, v96
	v_sub_f32_e32 v67, v67, v66
	v_fmac_f32_e32 v66, v67, v235
	v_lshlrev_b32_e32 v67, 16, v93
	v_lshlrev_b32_e32 v221, 16, v97
	v_cvt_pk_bf16_f32 v240, v240, v241
	v_cvt_pk_bf16_f32 v241, v242, v243
	v_sub_f32_e32 v221, v221, v67
	ds_write_b128 v161, v[238:241] offset:4608
	ds_write_b128 v161, v[88:91] offset:23040
	s_cmpk_eq_i32 s58, 0xf00
	s_cbranch_scc0 .Lrmp_Lrin_do_b
	s_waitcnt vmcnt(0)
	s_branch .Lrmp_Lrin_skip_b
.Lrmp_Lrin_do_b:
	v_lshl_add_u64 v[246:247], v[146:147], 0, v[186:187]
	global_load_dwordx4 v[80:83], v[246:247], off
	s_and_saveexec_b64 s[60:61], s[18:19]
	s_xor_b64 s[60:61], exec, s[60:61]
	s_cbranch_execz .Lrmp_b770
	v_lshl_add_u64 v[246:247], v[148:149], 0, v[186:187]
	global_load_dwordx4 v[84:87], v[246:247], off
.Lrmp_b770:
	s_andn2_saveexec_b64 s[60:61], s[60:61]
	s_cbranch_execz .Lrmp_b774
	s_waitcnt vmcnt(0)
	v_mov_b32_e32 v84, v64
	v_mov_b32_e32 v85, v64
	v_mov_b32_e32 v86, v64
	v_mov_b32_e32 v87, v64
	s_and_saveexec_b64 s[62:63], s[24:25]
	s_cbranch_execz .Lrmp_b773
	v_lshl_add_u64 v[246:247], v[196:197], 0, s[58:59]
	global_load_dwordx4 v[84:87], v[246:247], off offset:256
	global_load_dwordx4 v[88:91], v[246:247], off offset:272
	s_waitcnt vmcnt(1)
	v_cvt_pk_bf16_f32 v84, v84, v85
	v_cvt_pk_bf16_f32 v85, v86, v87
	s_waitcnt vmcnt(0)
	v_cvt_pk_bf16_f32 v86, v88, v89
	v_cvt_pk_bf16_f32 v87, v90, v91

.Lrmp_b774:
	s_or_b64 exec, exec, s[60:61]
	v_lshl_add_u64 v[246:247], v[136:137], 0, v[186:187]
	global_load_dwordx4 v[88:91], v[246:247], off
.Lrmp_Lrin_skip_b:
	v_fmac_f32_e32 v67, v221, v236
	v_and_b32_e32 v221, 0xffff0000, v93
	v_and_b32_e32 v238, 0xffff0000, v97
	v_sub_f32_e32 v238, v238, v221
	v_fmac_f32_e32 v221, v238, v237
	v_lshlrev_b32_e32 v240, 16, v94
	v_lshlrev_b32_e32 v238, 16, v98
	v_sub_f32_e32 v238, v238, v240
	v_fmac_f32_e32 v240, v238, v230
	v_and_b32_e32 v241, 0xffff0000, v94
	v_and_b32_e32 v238, 0xffff0000, v98
	v_sub_f32_e32 v238, v238, v241
	v_fmac_f32_e32 v241, v238, v231
	v_lshlrev_b32_e32 v242, 16, v95
	v_lshlrev_b32_e32 v238, 16, v99
	v_sub_f32_e32 v238, v238, v242
	v_fmac_f32_e32 v242, v238, v232
	v_and_b32_e32 v243, 0xffff0000, v95
	v_and_b32_e32 v238, 0xffff0000, v99
	v_sub_f32_e32 v238, v238, v243
	v_fmac_f32_e32 v243, v238, v233
	v_cvt_pk_bf16_f32 v238, v65, v66
	s_waitcnt vmcnt(6)
	v_lshlrev_b32_e32 v65, 16, v104
	v_lshlrev_b32_e32 v66, 16, v108
	v_sub_f32_e32 v66, v66, v65
	v_cvt_pk_bf16_f32 v239, v67, v221
	v_fmac_f32_e32 v65, v66, v234
	v_and_b32_e32 v66, 0xffff0000, v104
	v_and_b32_e32 v67, 0xffff0000, v108
	v_sub_f32_e32 v67, v67, v66
	v_fmac_f32_e32 v66, v67, v235
	v_lshlrev_b32_e32 v67, 16, v105
	v_lshlrev_b32_e32 v234, 16, v109
	v_sub_f32_e32 v234, v234, v67
	v_fmac_f32_e32 v67, v234, v236
	v_and_b32_e32 v234, 0xffff0000, v105
	v_and_b32_e32 v235, 0xffff0000, v109
	v_sub_f32_e32 v235, v235, v234
	v_fmac_f32_e32 v234, v235, v237
	v_lshlrev_b32_e32 v235, 16, v106
	v_lshlrev_b32_e32 v236, 16, v110
	v_sub_f32_e32 v236, v236, v235
	v_fmac_f32_e32 v235, v236, v230
	v_and_b32_e32 v236, 0xffff0000, v106
	v_and_b32_e32 v230, 0xffff0000, v110
	v_sub_f32_e32 v230, v230, v236
	v_fmac_f32_e32 v236, v230, v231
	v_lshlrev_b32_e32 v237, 16, v107
	v_lshlrev_b32_e32 v230, 16, v111
	v_sub_f32_e32 v230, v230, v237
	v_fmac_f32_e32 v237, v230, v232
	v_and_b32_e32 v221, 0xffff0000, v107
	v_and_b32_e32 v230, 0xffff0000, v111
	v_sub_f32_e32 v230, v230, v221
	v_cvt_pk_bf16_f32 v240, v240, v241
	v_cvt_pk_bf16_f32 v241, v242, v243
	v_fmac_f32_e32 v221, v230, v233
	v_cvt_pk_bf16_f32 v230, v65, v66
	v_cvt_pk_bf16_f32 v231, v67, v234
	v_cvt_pk_bf16_f32 v232, v235, v236
	v_cvt_pk_bf16_f32 v233, v237, v221
	ds_write_b128 v161, v[238:241] offset:9216
	ds_write_b128 v161, v[100:103] offset:27648
	ds_write_b128 v161, v[230:233] offset:13824
	ds_write_b128 v161, v[112:115] offset:32256
	s_cmpk_eq_i32 s58, 0xf00
	s_cbranch_scc0 .Lrmp_Lrin_do_c
	s_waitcnt vmcnt(0)
	s_branch .Lrmp_Lrin_skip_c
.Lrmp_Lrin_do_c:
	v_lshl_add_u64 v[246:247], v[150:151], 0, v[186:187]
	global_load_dwordx4 v[92:95], v[246:247], off
	s_and_saveexec_b64 s[60:61], s[20:21]
	s_xor_b64 s[60:61], exec, s[60:61]
	s_cbranch_execz .Lrmp_b776
	v_lshl_add_u64 v[246:247], v[188:189], 0, v[186:187]
	global_load_dwordx4 v[96:99], v[246:247], off
.Lrmp_b776:
	s_andn2_saveexec_b64 s[60:61], s[60:61]
	s_cbranch_execz .Lrmp_b780
	s_waitcnt vmcnt(0)
	v_mov_b32_e32 v96, v64
	v_mov_b32_e32 v97, v64
	v_mov_b32_e32 v98, v64
	v_mov_b32_e32 v99, v64
	s_and_saveexec_b64 s[62:63], s[26:27]
	s_cbranch_execz .Lrmp_b779
	v_lshl_add_u64 v[246:247], v[198:199], 0, s[58:59]
	global_load_dwordx4 v[96:99], v[246:247], off offset:256
	global_load_dwordx4 v[100:103], v[246:247], off offset:272
	s_waitcnt vmcnt(1)
	v_cvt_pk_bf16_f32 v96, v96, v97
	v_cvt_pk_bf16_f32 v97, v98, v99
	s_waitcnt vmcnt(0)
	v_cvt_pk_bf16_f32 v98, v100, v101
	v_cvt_pk_bf16_f32 v99, v102, v103

.Lrmp_b780:
	s_or_b64 exec, exec, s[60:61]
	v_lshl_add_u64 v[246:247], v[138:139], 0, v[186:187]
	global_load_dwordx4 v[100:103], v[246:247], off
	v_lshl_add_u64 v[246:247], v[190:191], 0, v[186:187]
	global_load_dwordx4 v[104:107], v[246:247], off
	s_and_saveexec_b64 s[60:61], s[22:23]
	s_xor_b64 s[60:61], exec, s[60:61]
	s_cbranch_execz .Lrmp_b782
	v_lshl_add_u64 v[246:247], v[192:193], 0, v[186:187]
	global_load_dwordx4 v[108:111], v[246:247], off
.Lrmp_b782:
	s_andn2_saveexec_b64 s[60:61], s[60:61]
	s_cbranch_execz .Lrmp_b759
	s_waitcnt vmcnt(0)
	v_mov_b32_e32 v108, v64
	v_mov_b32_e32 v109, v64
	v_mov_b32_e32 v110, v64
	v_mov_b32_e32 v111, v64
	s_and_saveexec_b64 s[62:63], s[28:29]
	s_cbranch_execz .Lrmp_b758
	v_lshl_add_u64 v[246:247], v[200:201], 0, s[58:59]
	global_load_dwordx4 v[108:111], v[246:247], off offset:256
	global_load_dwordx4 v[112:115], v[246:247], off offset:272
	s_waitcnt vmcnt(1)
	v_cvt_pk_bf16_f32 v108, v108, v109
	v_cvt_pk_bf16_f32 v109, v110, v111
	s_waitcnt vmcnt(0)
	v_cvt_pk_bf16_f32 v110, v112, v113
	v_cvt_pk_bf16_f32 v111, v114, v115

.Lrmp_b759:
	s_or_b64 exec, exec, s[60:61]
	v_lshl_add_u64 v[246:247], v[140:141], 0, v[186:187]
	global_load_dwordx4 v[112:115], v[246:247], off
.Lrmp_Lrin_skip_c:
	s_waitcnt lgkmcnt(0)
	s_barrier
.Lrin_even:
	s_add_u32 s58, s58, 0x100
	s_addc_u32 s59, s59, 0
	v_lshl_add_u64 v[134:135], v[134:135], 0, s[54:55]
	v_lshl_add_u64 v[136:137], v[136:137], 0, s[54:55]
	v_lshl_add_u64 v[138:139], v[138:139], 0, s[54:55]
	v_lshl_add_u64 v[140:141], v[140:141], 0, s[54:55]
	v_lshl_add_u64 v[142:143], v[142:143], 0, s[54:55]
	v_lshl_add_u64 v[144:145], v[144:145], 0, s[54:55]
	v_lshl_add_u64 v[146:147], v[146:147], 0, s[54:55]
	v_lshl_add_u64 v[148:149], v[148:149], 0, s[54:55]
	v_lshl_add_u64 v[150:151], v[150:151], 0, s[54:55]
	v_lshl_add_u64 v[188:189], v[188:189], 0, s[54:55]
	v_lshl_add_u64 v[190:191], v[190:191], 0, s[54:55]
	v_lshl_add_u64 v[192:193], v[192:193], 0, s[54:55]
	v_add_u32_e32 v161, 0x9000, v161
	ds_read_b128 v[116:119], v173 offset:18432
	ds_read_b128 v[120:123], v163
	ds_read_b128 v[222:225], v173 offset:23040
	ds_read_b128 v[226:229], v163 offset:4608
	ds_read_b128 v[230:233], v255 offset:16
	ds_read_b128 v[234:237], v255
	v_add_u32_e32 v255, 0x100, v255
	s_waitcnt vmcnt(9)
	v_lshlrev_b32_e32 v65, 16, v68
	v_lshlrev_b32_e32 v66, 16, v72
	v_sub_f32_e32 v66, v66, v65
	v_and_b32_e32 v67, 0xffff0000, v72
	v_lshlrev_b32_e32 v221, 16, v73
	v_and_b32_e32 v238, 0xffff0000, v73
	v_lshlrev_b32_e32 v240, 16, v70
	v_and_b32_e32 v241, 0xffff0000, v70
	v_lshlrev_b32_e32 v242, 16, v71
	v_and_b32_e32 v243, 0xffff0000, v71
	s_waitcnt vmcnt(6) lgkmcnt(0)
	v_mfma_f32_32x32x16_bf16 v[0:15], v[116:119], v[120:123], v[0:15]
	v_fmac_f32_e32 v65, v234, v66
	v_and_b32_e32 v66, 0xffff0000, v68
	v_sub_f32_e32 v67, v67, v66
	v_fmac_f32_e32 v66, v67, v235
	v_lshlrev_b32_e32 v67, 16, v69
	v_sub_f32_e32 v221, v221, v67
	v_fmac_f32_e32 v67, v221, v236
	v_and_b32_e32 v221, 0xffff0000, v69
	v_mfma_f32_32x32x16_bf16 v[48:63], v[222:225], v[120:123], v[48:63]
	v_sub_f32_e32 v238, v238, v221
	v_fmac_f32_e32 v221, v238, v237
	v_lshlrev_b32_e32 v238, 16, v74
	v_sub_f32_e32 v238, v238, v240
	v_fmac_f32_e32 v240, v238, v230
	v_and_b32_e32 v238, 0xffff0000, v74
	v_sub_f32_e32 v238, v238, v241
	v_fmac_f32_e32 v241, v238, v231
	v_mfma_f32_32x32x16_bf16 v[32:47], v[116:119], v[226:229], v[32:47]
	v_lshlrev_b32_e32 v238, 16, v75
	v_sub_f32_e32 v238, v238, v242
	v_fmac_f32_e32 v242, v238, v232
	v_and_b32_e32 v238, 0xffff0000, v75
	v_sub_f32_e32 v238, v238, v243
	v_fmac_f32_e32 v243, v238, v233
	v_cvt_pk_bf16_f32 v238, v65, v66
	v_lshlrev_b32_e32 v65, 16, v80
	v_mfma_f32_32x32x16_bf16 v[16:31], v[222:225], v[226:229], v[16:31]
	ds_read_b128 v[116:119], v173 offset:18464
	ds_read_b128 v[120:123], v163 offset:32
	ds_read_b128 v[222:225], v173 offset:23072
	ds_read_b128 v[226:229], v163 offset:4640
	v_lshlrev_b32_e32 v66, 16, v84
	v_sub_f32_e32 v66, v66, v65
	v_cvt_pk_bf16_f32 v239, v67, v221
	v_fmac_f32_e32 v65, v66, v234
	v_and_b32_e32 v66, 0xffff0000, v80
	v_and_b32_e32 v67, 0xffff0000, v84
	v_sub_f32_e32 v67, v67, v66
	v_fmac_f32_e32 v66, v67, v235
	v_lshlrev_b32_e32 v67, 16, v81
	v_lshlrev_b32_e32 v221, 16, v85
	v_cvt_pk_bf16_f32 v240, v240, v241
	v_cvt_pk_bf16_f32 v241, v242, v243
	v_sub_f32_e32 v221, v221, v67
	ds_write_b128 v161, v[238:241]
	ds_write_b128 v161, v[76:79] offset:18432
	s_cmpk_eq_i32 s58, 0xf00
	s_cbranch_scc0 .Lrme_Lrin_do_a
	s_waitcnt vmcnt(0)
	s_branch .Lrme_Lrin_skip_a

.Lrme_Lrin_skip_a:
	v_fmac_f32_e32 v67, v221, v236
	v_and_b32_e32 v221, 0xffff0000, v81
	v_and_b32_e32 v238, 0xffff0000, v85
	s_waitcnt lgkmcnt(2)
	v_mfma_f32_32x32x16_bf16 v[0:15], v[116:119], v[120:123], v[0:15]
	v_sub_f32_e32 v238, v238, v221
	v_fmac_f32_e32 v221, v238, v237
	v_lshlrev_b32_e32 v240, 16, v82
	v_lshlrev_b32_e32 v238, 16, v86
	v_sub_f32_e32 v238, v238, v240
	v_fmac_f32_e32 v240, v238, v230
	v_and_b32_e32 v241, 0xffff0000, v82
	v_and_b32_e32 v238, 0xffff0000, v86
	v_mfma_f32_32x32x16_bf16 v[48:63], v[222:225], v[120:123], v[48:63]
	v_sub_f32_e32 v238, v238, v241
	v_fmac_f32_e32 v241, v238, v231
	v_lshlrev_b32_e32 v242, 16, v83
	v_lshlrev_b32_e32 v238, 16, v87
	v_sub_f32_e32 v238, v238, v242
	v_fmac_f32_e32 v242, v238, v232
	v_and_b32_e32 v243, 0xffff0000, v83
	v_and_b32_e32 v238, 0xffff0000, v87
	v_mfma_f32_32x32x16_bf16 v[32:47], v[116:119], v[226:229], v[32:47]
	v_sub_f32_e32 v238, v238, v243
	v_fmac_f32_e32 v243, v238, v233
	v_cvt_pk_bf16_f32 v238, v65, v66
	s_waitcnt vmcnt(6)
	v_lshlrev_b32_e32 v65, 16, v92
	v_lshlrev_b32_e32 v66, 16, v96
	v_sub_f32_e32 v66, v66, v65
	v_cvt_pk_bf16_f32 v239, v67, v221
	v_fmac_f32_e32 v65, v66, v234
	v_mfma_f32_32x32x16_bf16 v[16:31], v[222:225], v[226:229], v[16:31]
	ds_read_b128 v[116:119], v173 offset:18496
	ds_read_b128 v[120:123], v163 offset:64
	ds_read_b128 v[222:225], v173 offset:23104
	ds_read_b128 v[226:229], v163 offset:4672
	v_and_b32_e32 v66, 0xffff0000, v92
	v_and_b32_e32 v67, 0xffff0000, v96
	v_sub_f32_e32 v67, v67, v66
	v_fmac_f32_e32 v66, v67, v235
	v_lshlrev_b32_e32 v67, 16, v93
	v_lshlrev_b32_e32 v221, 16, v97
	v_cvt_pk_bf16_f32 v240, v240, v241
	v_cvt_pk_bf16_f32 v241, v242, v243
	v_sub_f32_e32 v221, v221, v67
	ds_write_b128 v161, v[238:241] offset:4608
	ds_write_b128 v161, v[88:91] offset:23040
	s_cmpk_eq_i32 s58, 0xf00
	s_cbranch_scc0 .Lrme_Lrin_do_b
	s_waitcnt vmcnt(0)
	s_branch .Lrme_Lrin_skip_b

.Lrme_Lrin_skip_b:
	v_fmac_f32_e32 v67, v221, v236
	v_and_b32_e32 v221, 0xffff0000, v93
	v_and_b32_e32 v238, 0xffff0000, v97
	v_sub_f32_e32 v238, v238, v221
	v_fmac_f32_e32 v221, v238, v237
	v_lshlrev_b32_e32 v240, 16, v94
	v_lshlrev_b32_e32 v238, 16, v98
	s_waitcnt lgkmcnt(2)
	v_mfma_f32_32x32x16_bf16 v[0:15], v[116:119], v[120:123], v[0:15]
	v_sub_f32_e32 v238, v238, v240
	v_fmac_f32_e32 v240, v238, v230
	v_and_b32_e32 v241, 0xffff0000, v94
	v_and_b32_e32 v238, 0xffff0000, v98
	v_sub_f32_e32 v238, v238, v241
	v_fmac_f32_e32 v241, v238, v231
	v_lshlrev_b32_e32 v242, 16, v95
	v_lshlrev_b32_e32 v238, 16, v99
	v_mfma_f32_32x32x16_bf16 v[48:63], v[222:225], v[120:123], v[48:63]
	v_sub_f32_e32 v238, v238, v242
	v_fmac_f32_e32 v242, v238, v232
	v_and_b32_e32 v243, 0xffff0000, v95
	v_and_b32_e32 v238, 0xffff0000, v99
	v_sub_f32_e32 v238, v238, v243
	v_fmac_f32_e32 v243, v238, v233
	v_cvt_pk_bf16_f32 v238, v65, v66
	s_waitcnt vmcnt(6)
	v_lshlrev_b32_e32 v65, 16, v104
	v_mfma_f32_32x32x16_bf16 v[32:47], v[116:119], v[226:229], v[32:47]
	v_lshlrev_b32_e32 v66, 16, v108
	v_sub_f32_e32 v66, v66, v65
	v_cvt_pk_bf16_f32 v239, v67, v221
	v_fmac_f32_e32 v65, v66, v234
	v_and_b32_e32 v66, 0xffff0000, v104
	v_and_b32_e32 v67, 0xffff0000, v108
	v_sub_f32_e32 v67, v67, v66
	v_fmac_f32_e32 v66, v67, v235
	v_mfma_f32_32x32x16_bf16 v[16:31], v[222:225], v[226:229], v[16:31]
	ds_read_b128 v[116:119], v173 offset:18528
	ds_read_b128 v[120:123], v163 offset:96
	ds_read_b128 v[222:225], v173 offset:23136
	ds_read_b128 v[226:229], v163 offset:4704
	v_lshlrev_b32_e32 v67, 16, v105
	v_lshlrev_b32_e32 v234, 16, v109
	v_sub_f32_e32 v234, v234, v67
	v_fmac_f32_e32 v67, v234, v236
	v_and_b32_e32 v234, 0xffff0000, v105
	v_and_b32_e32 v235, 0xffff0000, v109
	v_sub_f32_e32 v235, v235, v234
	v_fmac_f32_e32 v234, v235, v237
	v_lshlrev_b32_e32 v235, 16, v106
	v_lshlrev_b32_e32 v236, 16, v110
	v_sub_f32_e32 v236, v236, v235
	v_fmac_f32_e32 v235, v236, v230
	v_and_b32_e32 v236, 0xffff0000, v106
	v_and_b32_e32 v230, 0xffff0000, v110
	v_sub_f32_e32 v230, v230, v236
	v_fmac_f32_e32 v236, v230, v231
	s_waitcnt lgkmcnt(0)
	v_mfma_f32_32x32x16_bf16 v[0:15], v[116:119], v[120:123], v[0:15]
	v_lshlrev_b32_e32 v237, 16, v107
	v_lshlrev_b32_e32 v230, 16, v111
	v_sub_f32_e32 v230, v230, v237
	v_fmac_f32_e32 v237, v230, v232
	v_and_b32_e32 v221, 0xffff0000, v107
	v_and_b32_e32 v230, 0xffff0000, v111
	v_sub_f32_e32 v230, v230, v221
	v_cvt_pk_bf16_f32 v240, v240, v241
	v_mfma_f32_32x32x16_bf16 v[48:63], v[222:225], v[120:123], v[48:63]
	v_cvt_pk_bf16_f32 v241, v242, v243
	v_fmac_f32_e32 v221, v230, v233
	v_cvt_pk_bf16_f32 v230, v65, v66
	v_cvt_pk_bf16_f32 v231, v67, v234
	v_cvt_pk_bf16_f32 v232, v235, v236
	v_cvt_pk_bf16_f32 v233, v237, v221
	ds_write_b128 v161, v[238:241] offset:9216
	ds_write_b128 v161, v[100:103] offset:27648
	ds_write_b128 v161, v[230:233] offset:13824
	ds_write_b128 v161, v[112:115] offset:32256
	s_cmpk_eq_i32 s58, 0xf00
	s_cbranch_scc0 .Lrme_Lrin_do_c
	s_waitcnt vmcnt(0)
	s_branch .Lrme_Lrin_skip_c

.Lrme_Lrin_skip_c:
	s_nop 3
	v_mfma_f32_32x32x16_bf16 v[32:47], v[116:119], v[226:229], v[32:47]
	v_mfma_f32_32x32x16_bf16 v[16:31], v[222:225], v[226:229], v[16:31]
	v_add_u32_e32 v161, 0xffff7000, v161
	s_waitcnt lgkmcnt(0)
	s_barrier
	s_cmpk_eq_i32 s58, 0xf00
	s_cbranch_scc1 .Lrin_tail
.Lrin_odd:
	s_add_u32 s58, s58, 0x100
	s_addc_u32 s59, s59, 0
	v_lshl_add_u64 v[134:135], v[134:135], 0, s[54:55]
	v_lshl_add_u64 v[136:137], v[136:137], 0, s[54:55]
	v_lshl_add_u64 v[138:139], v[138:139], 0, s[54:55]
	v_lshl_add_u64 v[140:141], v[140:141], 0, s[54:55]
	v_lshl_add_u64 v[142:143], v[142:143], 0, s[54:55]
	v_lshl_add_u64 v[144:145], v[144:145], 0, s[54:55]
	v_lshl_add_u64 v[146:147], v[146:147], 0, s[54:55]
	v_lshl_add_u64 v[148:149], v[148:149], 0, s[54:55]
	v_lshl_add_u64 v[150:151], v[150:151], 0, s[54:55]
	v_lshl_add_u64 v[188:189], v[188:189], 0, s[54:55]
	v_lshl_add_u64 v[190:191], v[190:191], 0, s[54:55]
	v_lshl_add_u64 v[192:193], v[192:193], 0, s[54:55]
	ds_read_b128 v[116:119], v173 offset:55296
	ds_read_b128 v[120:123], v163 offset:36864
	ds_read_b128 v[222:225], v173 offset:59904
	ds_read_b128 v[226:229], v163 offset:41472
	ds_read_b128 v[230:233], v255 offset:16
	ds_read_b128 v[234:237], v255
	v_add_u32_e32 v255, 0x100, v255
	s_waitcnt vmcnt(9)
	v_lshlrev_b32_e32 v65, 16, v68
	v_lshlrev_b32_e32 v66, 16, v72
	v_sub_f32_e32 v66, v66, v65
	v_and_b32_e32 v67, 0xffff0000, v72
	v_lshlrev_b32_e32 v221, 16, v73
	v_and_b32_e32 v238, 0xffff0000, v73
	v_lshlrev_b32_e32 v240, 16, v70
	v_and_b32_e32 v241, 0xffff0000, v70
	v_lshlrev_b32_e32 v242, 16, v71
	v_and_b32_e32 v243, 0xffff0000, v71
	s_waitcnt vmcnt(6) lgkmcnt(0)
	v_mfma_f32_32x32x16_bf16 v[0:15], v[116:119], v[120:123], v[0:15]
	v_fmac_f32_e32 v65, v234, v66
	v_and_b32_e32 v66, 0xffff0000, v68
	v_sub_f32_e32 v67, v67, v66
	v_fmac_f32_e32 v66, v67, v235
	v_lshlrev_b32_e32 v67, 16, v69
	v_sub_f32_e32 v221, v221, v67
	v_fmac_f32_e32 v67, v221, v236
	v_and_b32_e32 v221, 0xffff0000, v69
	v_mfma_f32_32x32x16_bf16 v[48:63], v[222:225], v[120:123], v[48:63]
	v_sub_f32_e32 v238, v238, v221
	v_fmac_f32_e32 v221, v238, v237
	v_lshlrev_b32_e32 v238, 16, v74
	v_sub_f32_e32 v238, v238, v240
	v_fmac_f32_e32 v240, v238, v230
	v_and_b32_e32 v238, 0xffff0000, v74
	v_sub_f32_e32 v238, v238, v241
	v_fmac_f32_e32 v241, v238, v231
	v_mfma_f32_32x32x16_bf16 v[32:47], v[116:119], v[226:229], v[32:47]
	v_lshlrev_b32_e32 v238, 16, v75
	v_sub_f32_e32 v238, v238, v242
	v_fmac_f32_e32 v242, v238, v232
	v_and_b32_e32 v238, 0xffff0000, v75
	v_sub_f32_e32 v238, v238, v243
	v_fmac_f32_e32 v243, v238, v233
	v_cvt_pk_bf16_f32 v238, v65, v66
	v_lshlrev_b32_e32 v65, 16, v80
	v_mfma_f32_32x32x16_bf16 v[16:31], v[222:225], v[226:229], v[16:31]
	ds_read_b128 v[116:119], v173 offset:55328
	ds_read_b128 v[120:123], v163 offset:36896
	ds_read_b128 v[222:225], v173 offset:59936
	ds_read_b128 v[226:229], v163 offset:41504
	v_lshlrev_b32_e32 v66, 16, v84
	v_sub_f32_e32 v66, v66, v65
	v_cvt_pk_bf16_f32 v239, v67, v221
	v_fmac_f32_e32 v65, v66, v234
	v_and_b32_e32 v66, 0xffff0000, v80
	v_and_b32_e32 v67, 0xffff0000, v84
	v_sub_f32_e32 v67, v67, v66
	v_fmac_f32_e32 v66, v67, v235
	v_lshlrev_b32_e32 v67, 16, v81
	v_lshlrev_b32_e32 v221, 16, v85
	v_cvt_pk_bf16_f32 v240, v240, v241
	v_cvt_pk_bf16_f32 v241, v242, v243
	v_sub_f32_e32 v221, v221, v67
	ds_write_b128 v161, v[238:241]
	ds_write_b128 v161, v[76:79] offset:18432
	s_cmpk_eq_i32 s58, 0xf00
	s_cbranch_scc0 .Lrmo_Lrin_do_a
	s_waitcnt vmcnt(0)
	s_branch .Lrmo_Lrin_skip_a

.Lrmo_Lrin_skip_a:
	v_fmac_f32_e32 v67, v221, v236
	v_and_b32_e32 v221, 0xffff0000, v81
	v_and_b32_e32 v238, 0xffff0000, v85
	s_waitcnt lgkmcnt(2)
	v_mfma_f32_32x32x16_bf16 v[0:15], v[116:119], v[120:123], v[0:15]
	v_sub_f32_e32 v238, v238, v221
	v_fmac_f32_e32 v221, v238, v237
	v_lshlrev_b32_e32 v240, 16, v82
	v_lshlrev_b32_e32 v238, 16, v86
	v_sub_f32_e32 v238, v238, v240
	v_fmac_f32_e32 v240, v238, v230
	v_and_b32_e32 v241, 0xffff0000, v82
	v_and_b32_e32 v238, 0xffff0000, v86
	v_mfma_f32_32x32x16_bf16 v[48:63], v[222:225], v[120:123], v[48:63]
	v_sub_f32_e32 v238, v238, v241
	v_fmac_f32_e32 v241, v238, v231
	v_lshlrev_b32_e32 v242, 16, v83
	v_lshlrev_b32_e32 v238, 16, v87
	v_sub_f32_e32 v238, v238, v242
	v_fmac_f32_e32 v242, v238, v232
	v_and_b32_e32 v243, 0xffff0000, v83
	v_and_b32_e32 v238, 0xffff0000, v87
	v_mfma_f32_32x32x16_bf16 v[32:47], v[116:119], v[226:229], v[32:47]
	v_sub_f32_e32 v238, v238, v243
	v_fmac_f32_e32 v243, v238, v233
	v_cvt_pk_bf16_f32 v238, v65, v66
	s_waitcnt vmcnt(6)
	v_lshlrev_b32_e32 v65, 16, v92
	v_lshlrev_b32_e32 v66, 16, v96
	v_sub_f32_e32 v66, v66, v65
	v_cvt_pk_bf16_f32 v239, v67, v221
	v_fmac_f32_e32 v65, v66, v234
	v_mfma_f32_32x32x16_bf16 v[16:31], v[222:225], v[226:229], v[16:31]
	ds_read_b128 v[116:119], v173 offset:55360
	ds_read_b128 v[120:123], v163 offset:36928
	ds_read_b128 v[222:225], v173 offset:59968
	ds_read_b128 v[226:229], v163 offset:41536
	v_and_b32_e32 v66, 0xffff0000, v92
	v_and_b32_e32 v67, 0xffff0000, v96
	v_sub_f32_e32 v67, v67, v66
	v_fmac_f32_e32 v66, v67, v235
	v_lshlrev_b32_e32 v67, 16, v93
	v_lshlrev_b32_e32 v221, 16, v97
	v_cvt_pk_bf16_f32 v240, v240, v241
	v_cvt_pk_bf16_f32 v241, v242, v243
	v_sub_f32_e32 v221, v221, v67
	ds_write_b128 v161, v[238:241] offset:4608
	ds_write_b128 v161, v[88:91] offset:23040
	s_cmpk_eq_i32 s58, 0xf00
	s_cbranch_scc0 .Lrmo_Lrin_do_b
	s_waitcnt vmcnt(0)
	s_branch .Lrmo_Lrin_skip_b

.Lrmo_Lrin_skip_b:
	v_fmac_f32_e32 v67, v221, v236
	v_and_b32_e32 v221, 0xffff0000, v93
	v_and_b32_e32 v238, 0xffff0000, v97
	v_sub_f32_e32 v238, v238, v221
	v_fmac_f32_e32 v221, v238, v237
	v_lshlrev_b32_e32 v240, 16, v94
	v_lshlrev_b32_e32 v238, 16, v98
	s_waitcnt lgkmcnt(2)
	v_mfma_f32_32x32x16_bf16 v[0:15], v[116:119], v[120:123], v[0:15]
	v_sub_f32_e32 v238, v238, v240
	v_fmac_f32_e32 v240, v238, v230
	v_and_b32_e32 v241, 0xffff0000, v94
	v_and_b32_e32 v238, 0xffff0000, v98
	v_sub_f32_e32 v238, v238, v241
	v_fmac_f32_e32 v241, v238, v231
	v_lshlrev_b32_e32 v242, 16, v95
	v_lshlrev_b32_e32 v238, 16, v99
	v_mfma_f32_32x32x16_bf16 v[48:63], v[222:225], v[120:123], v[48:63]
	v_sub_f32_e32 v238, v238, v242
	v_fmac_f32_e32 v242, v238, v232
	v_and_b32_e32 v243, 0xffff0000, v95
	v_and_b32_e32 v238, 0xffff0000, v99
	v_sub_f32_e32 v238, v238, v243
	v_fmac_f32_e32 v243, v238, v233
	v_cvt_pk_bf16_f32 v238, v65, v66
	s_waitcnt vmcnt(6)
	v_lshlrev_b32_e32 v65, 16, v104
	v_mfma_f32_32x32x16_bf16 v[32:47], v[116:119], v[226:229], v[32:47]
	v_lshlrev_b32_e32 v66, 16, v108
	v_sub_f32_e32 v66, v66, v65
	v_cvt_pk_bf16_f32 v239, v67, v221
	v_fmac_f32_e32 v65, v66, v234
	v_and_b32_e32 v66, 0xffff0000, v104
	v_and_b32_e32 v67, 0xffff0000, v108
	v_sub_f32_e32 v67, v67, v66
	v_fmac_f32_e32 v66, v67, v235
	v_mfma_f32_32x32x16_bf16 v[16:31], v[222:225], v[226:229], v[16:31]
	ds_read_b128 v[116:119], v173 offset:55392
	ds_read_b128 v[120:123], v163 offset:36960
	ds_read_b128 v[222:225], v173 offset:60000
	ds_read_b128 v[226:229], v163 offset:41568
	v_lshlrev_b32_e32 v67, 16, v105
	v_lshlrev_b32_e32 v234, 16, v109
	v_sub_f32_e32 v234, v234, v67
	v_fmac_f32_e32 v67, v234, v236
	v_and_b32_e32 v234, 0xffff0000, v105
	v_and_b32_e32 v235, 0xffff0000, v109
	v_sub_f32_e32 v235, v235, v234
	v_fmac_f32_e32 v234, v235, v237
	v_lshlrev_b32_e32 v235, 16, v106
	v_lshlrev_b32_e32 v236, 16, v110
	v_sub_f32_e32 v236, v236, v235
	v_fmac_f32_e32 v235, v236, v230
	v_and_b32_e32 v236, 0xffff0000, v106
	v_and_b32_e32 v230, 0xffff0000, v110
	v_sub_f32_e32 v230, v230, v236
	v_fmac_f32_e32 v236, v230, v231
	s_waitcnt lgkmcnt(0)
	v_mfma_f32_32x32x16_bf16 v[0:15], v[116:119], v[120:123], v[0:15]
	v_lshlrev_b32_e32 v237, 16, v107
	v_lshlrev_b32_e32 v230, 16, v111
	v_sub_f32_e32 v230, v230, v237
	v_fmac_f32_e32 v237, v230, v232
	v_and_b32_e32 v221, 0xffff0000, v107
	v_and_b32_e32 v230, 0xffff0000, v111
	v_sub_f32_e32 v230, v230, v221
	v_cvt_pk_bf16_f32 v240, v240, v241
	v_mfma_f32_32x32x16_bf16 v[48:63], v[222:225], v[120:123], v[48:63]
	v_cvt_pk_bf16_f32 v241, v242, v243
	v_fmac_f32_e32 v221, v230, v233
	v_cvt_pk_bf16_f32 v230, v65, v66
	v_cvt_pk_bf16_f32 v231, v67, v234
	v_cvt_pk_bf16_f32 v232, v235, v236
	v_cvt_pk_bf16_f32 v233, v237, v221
	ds_write_b128 v161, v[238:241] offset:9216
	ds_write_b128 v161, v[100:103] offset:27648
	ds_write_b128 v161, v[230:233] offset:13824
	ds_write_b128 v161, v[112:115] offset:32256
	s_cmpk_eq_i32 s58, 0xf00
	s_cbranch_scc0 .Lrmo_Lrin_do_c
	s_waitcnt vmcnt(0)
	s_branch .Lrmo_Lrin_skip_c

.Lrmo_Lrin_skip_c:
	s_nop 3
	v_mfma_f32_32x32x16_bf16 v[32:47], v[116:119], v[226:229], v[32:47]
	v_mfma_f32_32x32x16_bf16 v[16:31], v[222:225], v[226:229], v[16:31]
	s_waitcnt lgkmcnt(0)
	s_barrier
	s_branch .Lrin_even
.Lrin_tail:
	s_add_u32 s58, s58, 0x100
	s_addc_u32 s59, s59, 0
	ds_read_b128 v[116:119], v173 offset:55296
	ds_read_b128 v[120:123], v163 offset:36864
	ds_read_b128 v[222:225], v173 offset:59904
	ds_read_b128 v[226:229], v163 offset:41472
	s_waitcnt lgkmcnt(0)
	v_mfma_f32_32x32x16_bf16 v[0:15], v[116:119], v[120:123], v[0:15]
	v_mfma_f32_32x32x16_bf16 v[48:63], v[222:225], v[120:123], v[48:63]
	v_mfma_f32_32x32x16_bf16 v[32:47], v[116:119], v[226:229], v[32:47]
	v_mfma_f32_32x32x16_bf16 v[16:31], v[222:225], v[226:229], v[16:31]
	ds_read_b128 v[116:119], v173 offset:55328
	ds_read_b128 v[120:123], v163 offset:36896
	ds_read_b128 v[222:225], v173 offset:59936
	ds_read_b128 v[226:229], v163 offset:41504
	s_waitcnt lgkmcnt(0)
	v_mfma_f32_32x32x16_bf16 v[0:15], v[116:119], v[120:123], v[0:15]
	v_mfma_f32_32x32x16_bf16 v[48:63], v[222:225], v[120:123], v[48:63]
	v_mfma_f32_32x32x16_bf16 v[32:47], v[116:119], v[226:229], v[32:47]
	v_mfma_f32_32x32x16_bf16 v[16:31], v[222:225], v[226:229], v[16:31]
	ds_read_b128 v[116:119], v173 offset:55360
	ds_read_b128 v[120:123], v163 offset:36928
	ds_read_b128 v[222:225], v173 offset:59968
	ds_read_b128 v[226:229], v163 offset:41536
	s_waitcnt lgkmcnt(0)
	v_mfma_f32_32x32x16_bf16 v[0:15], v[116:119], v[120:123], v[0:15]
	v_mfma_f32_32x32x16_bf16 v[48:63], v[222:225], v[120:123], v[48:63]
	v_mfma_f32_32x32x16_bf16 v[32:47], v[116:119], v[226:229], v[32:47]
	v_mfma_f32_32x32x16_bf16 v[16:31], v[222:225], v[226:229], v[16:31]
	ds_read_b128 v[116:119], v173 offset:55392
	ds_read_b128 v[120:123], v163 offset:36960
	ds_read_b128 v[222:225], v173 offset:60000
	ds_read_b128 v[226:229], v163 offset:41568
	s_waitcnt lgkmcnt(0)
	v_mfma_f32_32x32x16_bf16 v[0:15], v[116:119], v[120:123], v[0:15]
	v_mfma_f32_32x32x16_bf16 v[48:63], v[222:225], v[120:123], v[48:63]
	v_mfma_f32_32x32x16_bf16 v[32:47], v[116:119], v[226:229], v[32:47]
	v_mfma_f32_32x32x16_bf16 v[16:31], v[222:225], v[226:229], v[16:31]
